# RG-LRU: sqrt(max(em,0)) uses hardware v_sqrt_f32 directly instead of the 16-instruction refined-sqrt expansion (f32 throughout)
# baseline (speedup 1.0000x reference)
; #define LAS __attribute__((address_space(3)))
; __device__ __forceinline__ float fast_exp2(float x) { return __builtin_amdgcn_exp2f(x); }
; __device__ __forceinline__ float sigmoidf_(float x) { return fast_rcp(1.0f + fast_exp2(-x * LOG2E)); }
; __device__ __forceinline__ int crow(int r, int hi) { return (r & 3) + 8 * (r >> 2) + 4 * hi; }
; __device__ __forceinline__ void rglru_unit(const Params& P, int l, int unit, LAS unsigned char* lds, bool dry = false) {
;     ...
;         bf16_t* gp = proj + O_GR + (rowb + t0 + 16 * ss) * XP + 128 * n + 64 * j + sc;
;         unsigned short gq[16];
; #pragma unroll
;         for (int k = 0; k < 16; ++k) gq[k] = gp[(size_t)k * XP];
;         __syncthreads();
;         f32x16 accr = {}, acci = {};
; #pragma unroll
;         for (int s = 0; s < 8; ++s) { const bf16x8 a = *(const LAS bf16x8*)(xc + (32 * tb + r32) * 272 + (16 * s + 8 * hi) * 2);
;             const bf16x8 wr_ = *(const LAS bf16x8*)(WB + (32 * cb + r32) * 272 + (16 * s + 8 * hi) * 2), wi_ = *(const LAS bf16x8*)(WB + (64 + 32 * cb + r32) * 272 + (16 * s + 8 * hi) * 2);
;             accr = __builtin_amdgcn_mfma_f32_32x32x16_bf16(a, wr_, accr, 0, 0, 0); acci = __builtin_amdgcn_mfma_f32_32x32x16_bf16(a, wi_, acci, 0, 0, 0); }
; #pragma unroll
;         for (int r = 0; r < 16; ++r) { const int tok = 32 * tb + crow(r, hi);
;             const float rr = sigmoidf_(accr[r] + br), ii = sigmoidf_(acci[r] + bi);
;             const float la = -rr * sp8; const float a = fast_exp2(la * LOG2E);
;             const float x2 = 2.0f * la;
;             const float em = -x2 * (1.0f + x2 * (0.5f + x2 * (0.16666667f + x2 * (0.041666668f + x2 * (0.0083333338f + x2 * 0.0013888889f)))));
;             const float mult = __builtin_sqrtf(fmaxf(em, 0.f));
;             const float xcv = bf2f(*(const LAS unsigned short*)(xc + tok * 272 + dch * 2));
;             Ab[tok * 64 + 32 * cb + r32] = a; Ub[tok * 64 + 32 * cb + r32] = mult * ii * xcv; }
.LBB0_367:
	v_lshl_add_u64 v[2:3], v[108:109], 0, s[22:23]
	v_add_co_u32_e32 v126, vcc, 0xae00000, v2
	s_add_u32 s22, s22, 0x40000
	s_nop 0
	v_addc_co_u32_e32 v127, vcc, 0, v3, vcc
	v_add_co_u32_e32 v124, vcc, 0xae01000, v2
	s_addc_u32 s23, s23, 0
	s_nop 0
	v_addc_co_u32_e32 v125, vcc, 0, v3, vcc
	v_add_co_u32_e32 v122, vcc, 0xae02000, v2
	s_cmp_lg_u32 s22, 0x400000
	s_nop 0
	v_addc_co_u32_e32 v123, vcc, 0, v3, vcc
	v_add_co_u32_e32 v120, vcc, 0xae03000, v2
	v_add_u32_e32 v110, 0x80, v110
	s_nop 0
	v_addc_co_u32_e32 v121, vcc, 0, v3, vcc
	v_add_co_u32_e32 v118, vcc, 0xae04000, v2
	global_load_ushort v207, v[126:127], off
	global_load_ushort v206, v[126:127], off offset:2048
	global_load_ushort v205, v[124:125], off
	global_load_ushort v204, v[124:125], off offset:2048
	global_load_ushort v203, v[122:123], off
	global_load_ushort v202, v[122:123], off offset:2048
	global_load_ushort v201, v[120:121], off
	global_load_ushort v200, v[120:121], off offset:2048
	v_addc_co_u32_e32 v119, vcc, 0, v3, vcc
	v_add_co_u32_e32 v116, vcc, 0xae05000, v2
	s_nop 1
	v_addc_co_u32_e32 v117, vcc, 0, v3, vcc
	v_add_co_u32_e32 v114, vcc, 0xae06000, v2
	s_nop 1
	v_addc_co_u32_e32 v115, vcc, 0, v3, vcc
	v_add_co_u32_e32 v112, vcc, 0xae07000, v2
	s_nop 1
	v_addc_co_u32_e32 v113, vcc, 0, v3, vcc
	global_load_ushort v199, v[118:119], off
	global_load_ushort v198, v[118:119], off offset:2048
	global_load_ushort v197, v[116:117], off
	global_load_ushort v196, v[116:117], off offset:2048
	global_load_ushort v195, v[114:115], off
	global_load_ushort v194, v[114:115], off offset:2048
	global_load_ushort v111, v[112:113], off
	global_load_ushort v1, v[112:113], off offset:2048
	s_waitcnt lgkmcnt(0)
	s_barrier
	ds_read_b128 v[2:5], v190
	ds_read_b128 v[6:9], v191
	s_waitcnt lgkmcnt(0)
	v_mfma_f32_32x32x16_bf16 v[18:33], v[2:5], v[6:9], 0
	ds_read_b128 v[6:9], v192
	ds_read_b128 v[208:211], v190 offset:32
	ds_read_b128 v[212:215], v191 offset:32
	s_waitcnt vmcnt(0)
	v_lshlrev_b32_e32 v1, 16, v1
	s_waitcnt lgkmcnt(2)
	v_mfma_f32_32x32x16_bf16 v[2:17], v[2:5], v[6:9], 0
	s_waitcnt lgkmcnt(0)
	v_mfma_f32_32x32x16_bf16 v[18:33], v[208:211], v[212:215], v[18:33]
	ds_read_b128 v[212:215], v192 offset:32
	s_waitcnt lgkmcnt(0)
	v_mfma_f32_32x32x16_bf16 v[2:17], v[208:211], v[212:215], v[2:17]
	ds_read_b128 v[208:211], v190 offset:64
	ds_read_b128 v[212:215], v191 offset:64
	s_waitcnt lgkmcnt(0)
	v_mfma_f32_32x32x16_bf16 v[18:33], v[208:211], v[212:215], v[18:33]
	ds_read_b128 v[212:215], v192 offset:64
	s_waitcnt lgkmcnt(0)
	v_mfma_f32_32x32x16_bf16 v[2:17], v[208:211], v[212:215], v[2:17]
	ds_read_b128 v[208:211], v190 offset:96
	ds_read_b128 v[212:215], v191 offset:96
	s_waitcnt lgkmcnt(0)
	v_mfma_f32_32x32x16_bf16 v[18:33], v[208:211], v[212:215], v[18:33]
	ds_read_b128 v[212:215], v192 offset:96
	s_waitcnt lgkmcnt(0)
	v_mfma_f32_32x32x16_bf16 v[2:17], v[208:211], v[212:215], v[2:17]
	ds_read_b128 v[208:211], v190 offset:128
	ds_read_b128 v[212:215], v191 offset:128
	s_waitcnt lgkmcnt(0)
	v_mfma_f32_32x32x16_bf16 v[18:33], v[208:211], v[212:215], v[18:33]
	ds_read_b128 v[212:215], v192 offset:128
	s_waitcnt lgkmcnt(0)
	v_mfma_f32_32x32x16_bf16 v[2:17], v[208:211], v[212:215], v[2:17]
	ds_read_b128 v[208:211], v190 offset:160
	ds_read_b128 v[212:215], v191 offset:160
	s_waitcnt lgkmcnt(0)
	v_mfma_f32_32x32x16_bf16 v[18:33], v[208:211], v[212:215], v[18:33]
	ds_read_b128 v[212:215], v192 offset:160
	s_waitcnt lgkmcnt(0)
	v_mfma_f32_32x32x16_bf16 v[2:17], v[208:211], v[212:215], v[2:17]
	ds_read_b128 v[208:211], v190 offset:192
	ds_read_b128 v[212:215], v191 offset:192
	s_waitcnt lgkmcnt(0)
	v_mfma_f32_32x32x16_bf16 v[18:33], v[208:211], v[212:215], v[18:33]
	ds_read_b128 v[212:215], v192 offset:192
	s_waitcnt lgkmcnt(0)
	v_mfma_f32_32x32x16_bf16 v[2:17], v[208:211], v[212:215], v[2:17]
	ds_read_b128 v[208:211], v190 offset:224
	ds_read_b128 v[212:215], v191 offset:224
	ds_read_b128 v[226:229], v192 offset:224
	s_waitcnt lgkmcnt(1)
	v_mfma_f32_32x32x16_bf16 v[18:33], v[208:211], v[212:215], v[18:33]
	s_waitcnt lgkmcnt(0)
	v_mfma_f32_32x32x16_bf16 v[2:17], v[208:211], v[226:229], v[2:17]
	s_nop 9
	v_add_f32_e32 v18, v128, v18
	v_mul_f32_e32 v18, 0xbfb8aa3b, v18
	v_exp_f32_e32 v18, v18
	v_add_f32_e32 v19, v128, v19
	v_mul_f32_e32 v19, 0xbfb8aa3b, v19
	v_exp_f32_e32 v19, v19
	v_add_f32_e32 v18, 1.0, v18
	v_rcp_f32_e64 v18, -v18
	v_add_f32_e32 v2, v129, v2
	v_mul_f32_e32 v2, 0xbfb8aa3b, v2
	v_exp_f32_e32 v2, v2
	v_mul_f32_e32 v18, v130, v18
	v_add_f32_e32 v86, v18, v18
	v_fmamk_f32 v87, v86, 0x3ab60b61, v218
	v_fmaak_f32 v87, v86, v87, 0x3d2aaaab
	v_fmaak_f32 v87, v86, v87, 0x3e2aaaab
	v_fma_f32 v87, v86, v87, 0.5
	v_fma_f32 v87, v86, v87, 1.0
	v_mul_f32_e64 v86, v87, -v86
	v_max_f32_e32 v86, 0, v86
	v_mul_f32_e32 v18, 0x3fb8aa3b, v18
	v_exp_f32_e32 v18, v18
	v_add_f32_e32 v2, 1.0, v2
	v_rcp_f32_e32 v2, v2
	v_add_f32_e32 v3, v129, v3
	v_mul_f32_e32 v3, 0xbfb8aa3b, v3
	v_exp_f32_e32 v3, v3
	v_add_f32_e32 v4, v129, v4
	v_mul_f32_e32 v4, 0xbfb8aa3b, v4
	v_exp_f32_e32 v4, v4
	v_sqrt_f32_e32 v86, v86
	ds_read_u16 v87, v193
	ds_read_u16 v88, v193 offset:272
	ds_read_u16 v182, v193 offset:544
	ds_read_u16 v183, v193 offset:816
	ds_read_u16 v184, v193 offset:2176
	ds_read_u16 v185, v193 offset:2448
	ds_read_u16 v208, v193 offset:2720
	ds_read_u16 v209, v193 offset:2992
	ds_write_b32 v134, v18 offset:34816
	v_add_f32_e32 v18, 1.0, v19
	v_rcp_f32_e64 v18, -v18
	s_waitcnt lgkmcnt(8)
; #define LAS __attribute__((address_space(3)))
; __device__ __forceinline__ float fast_exp2(float x) { return __builtin_amdgcn_exp2f(x); }
; __device__ __forceinline__ float sigmoidf_(float x) { return fast_rcp(1.0f + fast_exp2(-x * LOG2E)); }
; __device__ __forceinline__ int crow(int r, int hi) { return (r & 3) + 8 * (r >> 2) + 4 * hi; }
; __device__ __forceinline__ void rglru_unit(const Params& P, int l, int unit, LAS unsigned char* lds, bool dry = false) {
;     ...
;         for (int r = 0; r < 16; ++r) { const int tok = 32 * tb + crow(r, hi);
;             const float rr = sigmoidf_(accr[r] + br), ii = sigmoidf_(acci[r] + bi);
;             const float la = -rr * sp8; const float a = fast_exp2(la * LOG2E);
;             const float x2 = 2.0f * la;
;             const float em = -x2 * (1.0f + x2 * (0.5f + x2 * (0.16666667f + x2 * (0.041666668f + x2 * (0.0083333338f + x2 * 0.0013888889f)))));
;             const float mult = __builtin_sqrtf(fmaxf(em, 0.f));
;             const float xcv = bf2f(*(const LAS unsigned short*)(xc + tok * 272 + dch * 2));
;             Ab[tok * 64 + 32 * cb + r32] = a; Ub[tok * 64 + 32 * cb + r32] = mult * ii * xcv; }
	v_lshlrev_b32_e32 v87, 16, v87
	v_mul_f32_e32 v2, v2, v86
	v_mul_f32_e32 v2, v2, v87
	ds_write_b32 v135, v2
	v_add_f32_e32 v2, 1.0, v3
	v_mul_f32_e32 v3, v130, v18
	v_add_f32_e32 v18, v3, v3
	v_fmamk_f32 v19, v18, 0x3ab60b61, v218
	v_fmaak_f32 v19, v18, v19, 0x3d2aaaab
	v_fmaak_f32 v19, v18, v19, 0x3e2aaaab
	v_fma_f32 v19, v18, v19, 0.5
	v_fma_f32 v19, v18, v19, 1.0
	v_mul_f32_e64 v18, v19, -v18
	v_max_f32_e32 v18, 0, v18
	v_mul_f32_e32 v3, 0x3fb8aa3b, v3
	v_exp_f32_e32 v3, v3
	v_rcp_f32_e32 v2, v2
	ds_write_b32 v136, v3 offset:34816
	s_nop 0
	s_nop 1
	v_sqrt_f32_e32 v18, v18
	v_add_f32_e32 v19, v128, v20
	v_mul_f32_e32 v19, 0xbfb8aa3b, v19
	v_exp_f32_e32 v19, v19
	s_waitcnt lgkmcnt(9)
	v_lshlrev_b32_e32 v20, 16, v88
	v_mul_f32_e32 v2, v2, v18
	v_mul_f32_e32 v2, v2, v20
	v_add_f32_e32 v3, 1.0, v19
	v_rcp_f32_e64 v3, -v3
	ds_write_b32 v137, v2
	v_add_f32_e32 v2, 1.0, v4
	v_rcp_f32_e32 v2, v2
	v_mul_f32_e32 v3, v130, v3
	v_add_f32_e32 v4, v3, v3
	v_fmamk_f32 v18, v4, 0x3ab60b61, v218
	v_fmaak_f32 v18, v4, v18, 0x3d2aaaab
	v_fmaak_f32 v18, v4, v18, 0x3e2aaaab
	v_fma_f32 v18, v4, v18, 0.5
	v_fma_f32 v18, v4, v18, 1.0
	v_mul_f32_e64 v4, v18, -v4
	v_max_f32_e32 v4, 0, v4
	v_mul_f32_e32 v3, 0x3fb8aa3b, v3
	v_exp_f32_e32 v3, v3
	ds_write_b32 v138, v3 offset:34816
	s_nop 0
	s_waitcnt lgkmcnt(10)
	v_lshlrev_b32_e32 v19, 16, v182
	v_sqrt_f32_e32 v4, v4
	v_add_f32_e32 v18, v128, v21
	v_mul_f32_e32 v18, 0xbfb8aa3b, v18
	v_exp_f32_e32 v18, v18
	v_mul_f32_e32 v2, v2, v4
	v_add_f32_e32 v4, v129, v5
	v_mul_f32_e32 v4, 0xbfb8aa3b, v4
	v_add_f32_e32 v3, 1.0, v18
	v_rcp_f32_e64 v3, -v3
	v_exp_f32_e32 v4, v4
	v_mul_f32_e32 v2, v2, v19
	ds_write_b32 v139, v2
	v_mul_f32_e32 v3, v130, v3
	v_add_f32_e32 v2, 1.0, v4
	v_add_f32_e32 v4, v3, v3
	v_fmamk_f32 v5, v4, 0x3ab60b61, v218
	v_fmaak_f32 v5, v4, v5, 0x3d2aaaab
	v_fmaak_f32 v5, v4, v5, 0x3e2aaaab
	v_fma_f32 v5, v4, v5, 0.5
	v_fma_f32 v5, v4, v5, 1.0
	v_mul_f32_e64 v4, v5, -v4
	v_max_f32_e32 v4, 0, v4
	v_mul_f32_e32 v3, 0x3fb8aa3b, v3
	v_rcp_f32_e32 v2, v2
	v_exp_f32_e32 v3, v3
	ds_write_b32 v140, v3 offset:34816
	s_waitcnt lgkmcnt(11)
	v_lshlrev_b32_e32 v18, 16, v183
	v_sqrt_f32_e32 v4, v4
	v_add_f32_e32 v5, v128, v22
	v_mul_f32_e32 v5, 0xbfb8aa3b, v5
	v_exp_f32_e32 v5, v5
	v_mul_f32_e32 v2, v2, v4
	v_add_f32_e32 v4, v129, v6
	v_mul_f32_e32 v4, 0xbfb8aa3b, v4
	v_add_f32_e32 v3, 1.0, v5
	v_rcp_f32_e64 v3, -v3
	v_exp_f32_e32 v4, v4
	v_mul_f32_e32 v2, v2, v18
	ds_write_b32 v141, v2
	v_mul_f32_e32 v3, v130, v3
	v_add_f32_e32 v2, 1.0, v4
	v_add_f32_e32 v4, v3, v3
	v_fmamk_f32 v5, v4, 0x3ab60b61, v218
	v_fmaak_f32 v5, v4, v5, 0x3d2aaaab
	v_fmaak_f32 v5, v4, v5, 0x3e2aaaab
	v_fma_f32 v5, v4, v5, 0.5
	v_fma_f32 v5, v4, v5, 1.0
	v_mul_f32_e64 v4, v5, -v4
	v_max_f32_e32 v4, 0, v4
	v_mul_f32_e32 v3, 0x3fb8aa3b, v3
	v_rcp_f32_e32 v2, v2
	v_exp_f32_e32 v3, v3
	ds_write_b32 v142, v3 offset:34816
	s_waitcnt lgkmcnt(12)
	v_lshlrev_b32_e32 v6, 16, v184
	v_sqrt_f32_e32 v4, v4
	v_add_f32_e32 v5, v128, v23
	v_mul_f32_e32 v5, 0xbfb8aa3b, v5
	v_exp_f32_e32 v5, v5
	v_mul_f32_e32 v2, v2, v4
	v_add_f32_e32 v4, v129, v7
	v_mul_f32_e32 v4, 0xbfb8aa3b, v4
	v_add_f32_e32 v3, 1.0, v5
	v_rcp_f32_e64 v3, -v3
	v_exp_f32_e32 v4, v4
	v_mul_f32_e32 v2, v2, v6
	ds_write_b32 v143, v2
	v_mul_f32_e32 v3, v130, v3
	v_add_f32_e32 v2, 1.0, v4
	v_add_f32_e32 v4, v3, v3
	v_fmamk_f32 v5, v4, 0x3ab60b61, v218
	v_fmaak_f32 v5, v4, v5, 0x3d2aaaab
	v_fmaak_f32 v5, v4, v5, 0x3e2aaaab
	v_fma_f32 v5, v4, v5, 0.5
	v_fma_f32 v5, v4, v5, 1.0
	v_mul_f32_e64 v4, v5, -v4
	v_max_f32_e32 v4, 0, v4
	v_mul_f32_e32 v3, 0x3fb8aa3b, v3
	v_rcp_f32_e32 v2, v2
	v_exp_f32_e32 v3, v3
	ds_write_b32 v144, v3 offset:34816
	s_waitcnt lgkmcnt(13)
	v_lshlrev_b32_e32 v6, 16, v185
	v_sqrt_f32_e32 v4, v4
	v_add_f32_e32 v5, v128, v24
	v_mul_f32_e32 v5, 0xbfb8aa3b, v5
	v_exp_f32_e32 v5, v5
	v_mul_f32_e32 v2, v2, v4
	v_add_f32_e32 v4, v129, v8
	v_mul_f32_e32 v4, 0xbfb8aa3b, v4
	v_add_f32_e32 v3, 1.0, v5
	v_rcp_f32_e64 v3, -v3
	v_exp_f32_e32 v4, v4
	v_mul_f32_e32 v2, v2, v6
	ds_write_b32 v145, v2
	v_mul_f32_e32 v3, v130, v3
	v_add_f32_e32 v2, 1.0, v4
	v_add_f32_e32 v4, v3, v3
	v_fmamk_f32 v5, v4, 0x3ab60b61, v218
	v_fmaak_f32 v5, v4, v5, 0x3d2aaaab
	v_fmaak_f32 v5, v4, v5, 0x3e2aaaab
	v_fma_f32 v5, v4, v5, 0.5
	v_fma_f32 v5, v4, v5, 1.0
	v_mul_f32_e64 v4, v5, -v4
	v_max_f32_e32 v4, 0, v4
	v_mul_f32_e32 v3, 0x3fb8aa3b, v3
	v_rcp_f32_e32 v2, v2
	v_exp_f32_e32 v3, v3
	ds_write_b32 v146, v3 offset:34816
	s_waitcnt lgkmcnt(14)
	v_lshlrev_b32_e32 v6, 16, v208
	v_sqrt_f32_e32 v4, v4
	v_add_f32_e32 v5, v128, v25
	v_mul_f32_e32 v5, 0xbfb8aa3b, v5
	v_exp_f32_e32 v5, v5
	v_mul_f32_e32 v2, v2, v4
	v_add_f32_e32 v4, v129, v9
	v_mul_f32_e32 v4, 0xbfb8aa3b, v4
	v_add_f32_e32 v3, 1.0, v5
	v_rcp_f32_e64 v3, -v3
	v_exp_f32_e32 v4, v4
	v_mul_f32_e32 v2, v2, v6
	ds_write_b32 v147, v2
	v_mul_f32_e32 v3, v130, v3
	v_add_f32_e32 v2, 1.0, v4
	v_add_f32_e32 v4, v3, v3
	v_fmamk_f32 v5, v4, 0x3ab60b61, v218
	v_fmaak_f32 v5, v4, v5, 0x3d2aaaab
	v_fmaak_f32 v5, v4, v5, 0x3e2aaaab
	v_fma_f32 v5, v4, v5, 0.5
	v_fma_f32 v5, v4, v5, 1.0
	v_mul_f32_e64 v4, v5, -v4
	v_max_f32_e32 v4, 0, v4
	v_mul_f32_e32 v3, 0x3fb8aa3b, v3
	v_rcp_f32_e32 v2, v2
	v_exp_f32_e32 v3, v3
	ds_write_b32 v148, v3 offset:34816
	s_waitcnt lgkmcnt(14)
; #define LAS __attribute__((address_space(3)))
; __device__ __forceinline__ float fast_exp2(float x) { return __builtin_amdgcn_exp2f(x); }
; __device__ __forceinline__ float sigmoidf_(float x) { return fast_rcp(1.0f + fast_exp2(-x * LOG2E)); }
; __device__ __forceinline__ int crow(int r, int hi) { return (r & 3) + 8 * (r >> 2) + 4 * hi; }
; __device__ __forceinline__ void rglru_unit(const Params& P, int l, int unit, LAS unsigned char* lds, bool dry = false) {
;     ...
;         for (int r = 0; r < 16; ++r) { const int tok = 32 * tb + crow(r, hi);
;             const float rr = sigmoidf_(accr[r] + br), ii = sigmoidf_(acci[r] + bi);
;             const float la = -rr * sp8; const float a = fast_exp2(la * LOG2E);
;             const float x2 = 2.0f * la;
;             const float em = -x2 * (1.0f + x2 * (0.5f + x2 * (0.16666667f + x2 * (0.041666668f + x2 * (0.0083333338f + x2 * 0.0013888889f)))));
;             const float mult = __builtin_sqrtf(fmaxf(em, 0.f));
;             const float xcv = bf2f(*(const LAS unsigned short*)(xc + tok * 272 + dch * 2));
;             Ab[tok * 64 + 32 * cb + r32] = a; Ub[tok * 64 + 32 * cb + r32] = mult * ii * xcv; }
;         __syncthreads();
	v_lshlrev_b32_e32 v6, 16, v209
	v_sqrt_f32_e32 v4, v4
	v_add_f32_e32 v5, v128, v26
	v_mul_f32_e32 v5, 0xbfb8aa3b, v5
	v_exp_f32_e32 v5, v5
	v_mul_f32_e32 v2, v2, v4
	v_add_f32_e32 v4, v129, v10
	v_mul_f32_e32 v4, 0xbfb8aa3b, v4
	v_add_f32_e32 v3, 1.0, v5
	v_rcp_f32_e64 v3, -v3
	v_exp_f32_e32 v4, v4
	v_mul_f32_e32 v2, v2, v6
	ds_write_b32 v149, v2
	v_mul_f32_e32 v3, v130, v3
	v_add_f32_e32 v2, 1.0, v4
	v_add_f32_e32 v4, v3, v3
	v_fmamk_f32 v5, v4, 0x3ab60b61, v218
	v_fmaak_f32 v5, v4, v5, 0x3d2aaaab
	v_fmaak_f32 v5, v4, v5, 0x3e2aaaab
	v_fma_f32 v5, v4, v5, 0.5
	v_fma_f32 v5, v4, v5, 1.0
	v_mul_f32_e64 v4, v5, -v4
	v_max_f32_e32 v4, 0, v4
	v_mul_f32_e32 v3, 0x3fb8aa3b, v3
	v_rcp_f32_e32 v2, v2
	v_exp_f32_e32 v3, v3
	s_nop 0
	ds_read_u16 v6, v193 offset:4352
	ds_read_u16 v7, v193 offset:4624
	ds_read_u16 v8, v193 offset:4896
	ds_read_u16 v9, v193 offset:5168
	ds_read_u16 v10, v193 offset:6528
	ds_read_u16 v18, v193 offset:6800
	ds_read_u16 v19, v193 offset:7072
	ds_read_u16 v20, v193 offset:7344
	v_sqrt_f32_e32 v4, v4
	v_add_f32_e32 v5, v128, v27
	v_mul_f32_e32 v5, 0xbfb8aa3b, v5
	v_exp_f32_e32 v5, v5
	ds_write_b32 v150, v3 offset:34816
	v_mul_f32_e32 v2, v2, v4
	v_add_f32_e32 v4, v129, v11
	v_add_f32_e32 v3, 1.0, v5
	v_mul_f32_e32 v4, 0xbfb8aa3b, v4
	v_rcp_f32_e64 v3, -v3
	v_exp_f32_e32 v4, v4
	s_waitcnt lgkmcnt(8)
	v_lshlrev_b32_e32 v6, 16, v6
	v_mul_f32_e32 v2, v2, v6
	v_mul_f32_e32 v3, v130, v3
	ds_write_b32 v151, v2
	v_add_f32_e32 v2, 1.0, v4
	v_add_f32_e32 v4, v3, v3
	v_fmamk_f32 v5, v4, 0x3ab60b61, v218
	v_fmaak_f32 v5, v4, v5, 0x3d2aaaab
	v_fmaak_f32 v5, v4, v5, 0x3e2aaaab
	v_fma_f32 v5, v4, v5, 0.5
	v_fma_f32 v5, v4, v5, 1.0
	v_mul_f32_e64 v4, v5, -v4
	v_max_f32_e32 v4, 0, v4
	v_mul_f32_e32 v3, 0x3fb8aa3b, v3
	v_rcp_f32_e32 v2, v2
	v_exp_f32_e32 v3, v3
	ds_write_b32 v152, v3 offset:34816
	s_waitcnt lgkmcnt(9)
	v_lshlrev_b32_e32 v6, 16, v7
	v_sqrt_f32_e32 v4, v4
	v_add_f32_e32 v5, v128, v28
	v_mul_f32_e32 v5, 0xbfb8aa3b, v5
	v_exp_f32_e32 v5, v5
	v_mul_f32_e32 v2, v2, v4
	v_add_f32_e32 v4, v129, v12
	v_mul_f32_e32 v4, 0xbfb8aa3b, v4
	v_add_f32_e32 v3, 1.0, v5
	v_rcp_f32_e64 v3, -v3
	v_exp_f32_e32 v4, v4
	v_mul_f32_e32 v2, v2, v6
	ds_write_b32 v153, v2
	v_mul_f32_e32 v3, v130, v3
	v_add_f32_e32 v2, 1.0, v4
	v_add_f32_e32 v4, v3, v3
	v_fmamk_f32 v5, v4, 0x3ab60b61, v218
	v_fmaak_f32 v5, v4, v5, 0x3d2aaaab
	v_fmaak_f32 v5, v4, v5, 0x3e2aaaab
	v_fma_f32 v5, v4, v5, 0.5
	v_fma_f32 v5, v4, v5, 1.0
	v_mul_f32_e64 v4, v5, -v4
	v_max_f32_e32 v4, 0, v4
	v_mul_f32_e32 v3, 0x3fb8aa3b, v3
	v_rcp_f32_e32 v2, v2
	v_exp_f32_e32 v3, v3
	ds_write_b32 v154, v3 offset:34816
	s_waitcnt lgkmcnt(10)
	v_lshlrev_b32_e32 v6, 16, v8
	v_sqrt_f32_e32 v4, v4
	v_add_f32_e32 v5, v128, v29
	v_mul_f32_e32 v5, 0xbfb8aa3b, v5
	v_exp_f32_e32 v5, v5
	v_mul_f32_e32 v2, v2, v4
	v_add_f32_e32 v4, v129, v13
	v_mul_f32_e32 v4, 0xbfb8aa3b, v4
	v_add_f32_e32 v3, 1.0, v5
	v_rcp_f32_e64 v3, -v3
	v_exp_f32_e32 v4, v4
	v_mul_f32_e32 v2, v2, v6
	ds_write_b32 v155, v2
	v_mul_f32_e32 v3, v130, v3
	v_add_f32_e32 v2, 1.0, v4
	v_add_f32_e32 v4, v3, v3
	v_fmamk_f32 v5, v4, 0x3ab60b61, v218
	v_fmaak_f32 v5, v4, v5, 0x3d2aaaab
	v_fmaak_f32 v5, v4, v5, 0x3e2aaaab
	v_fma_f32 v5, v4, v5, 0.5
	v_fma_f32 v5, v4, v5, 1.0
	v_mul_f32_e64 v4, v5, -v4
	v_max_f32_e32 v4, 0, v4
	v_mul_f32_e32 v3, 0x3fb8aa3b, v3
	v_rcp_f32_e32 v2, v2
	v_exp_f32_e32 v3, v3
	ds_write_b32 v156, v3 offset:34816
	s_waitcnt lgkmcnt(11)
	v_lshlrev_b32_e32 v6, 16, v9
	v_sqrt_f32_e32 v4, v4
	v_add_f32_e32 v5, v128, v30
	v_mul_f32_e32 v5, 0xbfb8aa3b, v5
	v_exp_f32_e32 v5, v5
	v_mul_f32_e32 v2, v2, v4
	v_add_f32_e32 v4, v129, v14
	v_mul_f32_e32 v4, 0xbfb8aa3b, v4
	v_add_f32_e32 v3, 1.0, v5
	v_rcp_f32_e64 v3, -v3
	v_exp_f32_e32 v4, v4
	v_mul_f32_e32 v2, v2, v6
	ds_write_b32 v157, v2
	v_mul_f32_e32 v3, v130, v3
	v_add_f32_e32 v2, 1.0, v4
	v_add_f32_e32 v4, v3, v3
	v_fmamk_f32 v5, v4, 0x3ab60b61, v218
	v_fmaak_f32 v5, v4, v5, 0x3d2aaaab
	v_fmaak_f32 v5, v4, v5, 0x3e2aaaab
	v_fma_f32 v5, v4, v5, 0.5
	v_fma_f32 v5, v4, v5, 1.0
	v_mul_f32_e64 v4, v5, -v4
	v_max_f32_e32 v4, 0, v4
	v_mul_f32_e32 v3, 0x3fb8aa3b, v3
	v_rcp_f32_e32 v2, v2
	v_exp_f32_e32 v3, v3
	ds_write_b32 v158, v3 offset:34816
	s_waitcnt lgkmcnt(12)
	v_lshlrev_b32_e32 v6, 16, v10
	v_sqrt_f32_e32 v4, v4
	v_add_f32_e32 v5, v128, v31
	v_mul_f32_e32 v5, 0xbfb8aa3b, v5
	v_exp_f32_e32 v5, v5
	v_mul_f32_e32 v2, v2, v4
	v_add_f32_e32 v4, v129, v15
	v_mul_f32_e32 v4, 0xbfb8aa3b, v4
	v_add_f32_e32 v3, 1.0, v5
	v_rcp_f32_e64 v3, -v3
	v_exp_f32_e32 v4, v4
	v_mul_f32_e32 v2, v2, v6
	ds_write_b32 v159, v2
	v_mul_f32_e32 v3, v130, v3
	v_add_f32_e32 v2, 1.0, v4
	v_add_f32_e32 v4, v3, v3
	v_fmamk_f32 v5, v4, 0x3ab60b61, v218
	v_fmaak_f32 v5, v4, v5, 0x3d2aaaab
	v_fmaak_f32 v5, v4, v5, 0x3e2aaaab
	v_fma_f32 v5, v4, v5, 0.5
	v_fma_f32 v5, v4, v5, 1.0
	v_mul_f32_e64 v4, v5, -v4
	v_max_f32_e32 v4, 0, v4
	v_mul_f32_e32 v3, 0x3fb8aa3b, v3
	v_rcp_f32_e32 v2, v2
	v_exp_f32_e32 v3, v3
	ds_write_b32 v160, v3 offset:34816
	s_waitcnt lgkmcnt(13)
	v_lshlrev_b32_e32 v6, 16, v18
	v_sqrt_f32_e32 v4, v4
	v_add_f32_e32 v5, v128, v32
	v_mul_f32_e32 v5, 0xbfb8aa3b, v5
	v_exp_f32_e32 v5, v5
	v_mul_f32_e32 v2, v2, v4
	v_add_f32_e32 v4, v129, v16
	v_mul_f32_e32 v4, 0xbfb8aa3b, v4
	v_add_f32_e32 v3, 1.0, v5
	v_rcp_f32_e64 v3, -v3
	v_exp_f32_e32 v4, v4
	v_mul_f32_e32 v2, v2, v6
	ds_write_b32 v161, v2
	v_mul_f32_e32 v3, v130, v3
	v_add_f32_e32 v2, 1.0, v4
	v_add_f32_e32 v4, v3, v3
	v_fmamk_f32 v5, v4, 0x3ab60b61, v218
	v_fmaak_f32 v5, v4, v5, 0x3d2aaaab
	v_fmaak_f32 v5, v4, v5, 0x3e2aaaab
	v_fma_f32 v5, v4, v5, 0.5
	v_fma_f32 v5, v4, v5, 1.0
	v_mul_f32_e64 v4, v5, -v4
	v_max_f32_e32 v4, 0, v4
	v_mul_f32_e32 v3, 0x3fb8aa3b, v3
	v_rcp_f32_e32 v2, v2
	v_exp_f32_e32 v3, v3
	ds_write_b32 v162, v3 offset:34816
	s_waitcnt lgkmcnt(14)
	v_lshlrev_b32_e32 v6, 16, v19
	v_sqrt_f32_e32 v4, v4
	v_add_f32_e32 v5, v128, v33
	v_mul_f32_e32 v5, 0xbfb8aa3b, v5
	v_exp_f32_e32 v5, v5
	v_mul_f32_e32 v2, v2, v4
	v_add_f32_e32 v4, v129, v17
	v_mul_f32_e32 v4, 0xbfb8aa3b, v4
	v_add_f32_e32 v3, 1.0, v5
	v_rcp_f32_e64 v3, -v3
	v_exp_f32_e32 v4, v4
	v_mul_f32_e32 v2, v2, v6
	ds_write_b32 v163, v2
	v_mul_f32_e32 v3, v130, v3
	v_add_f32_e32 v2, 1.0, v4
	v_add_f32_e32 v4, v3, v3
	v_fmamk_f32 v5, v4, 0x3ab60b61, v218
	v_fmaak_f32 v5, v4, v5, 0x3d2aaaab
	v_fmaak_f32 v5, v4, v5, 0x3e2aaaab
	v_fma_f32 v5, v4, v5, 0.5
	v_fma_f32 v5, v4, v5, 1.0
	v_mul_f32_e64 v4, v5, -v4
	v_max_f32_e32 v4, 0, v4
	v_rcp_f32_e32 v2, v2
	v_mul_f32_e32 v3, 0x3fb8aa3b, v3
	v_exp_f32_e32 v3, v3
	ds_write_b32 v164, v3 offset:34816
	s_nop 1
	v_sqrt_f32_e32 v4, v4
	s_waitcnt lgkmcnt(14)
	v_lshlrev_b32_e32 v5, 16, v20
	v_mul_f32_e32 v2, v2, v4
	v_mul_f32_e32 v2, v2, v5
	ds_write_b32 v165, v2
	s_waitcnt lgkmcnt(0)
	s_barrier
; __device__ __forceinline__ void rglru_unit(const Params& P, int l, int unit, LAS unsigned char* lds, bool dry = false) {
;     ...
;         { const int c = sc, s = ss;
;           float As = 1.f, Hs = 0.f;
; #pragma unroll
;           for (int k = 0; k < 16; ++k) { const float a = Ab[(16 * s + k) * 64 + c], u = Ub[(16 * s + k) * 64 + c]; Hs = a * Hs + u; As *= a; }
;           seg[s * 64 + c] = (f32x2){As, Hs};
;           __syncthreads();
	ds_read2st64_b32 v[2:3], v133 offset0:136 offset1:137
	ds_read2st64_b32 v[4:5], v133 offset0:138 offset1:139
	ds_read2st64_b32 v[6:7], v133 offset0:140 offset1:141
	ds_read2st64_b32 v[8:9], v133 offset0:142 offset1:143
	ds_read_b32 v10, v166
	ds_read_b32 v11, v167
	ds_read_b32 v12, v168
	ds_read_b32 v13, v169
	ds_read_b32 v14, v170
	ds_read_b32 v15, v171
	ds_read_b32 v16, v172
	ds_read_b32 v18, v173
	s_waitcnt lgkmcnt(7)
	v_fmac_f32_e32 v10, 0, v2
	s_waitcnt lgkmcnt(6)
	v_fmac_f32_e32 v11, v10, v3
	s_waitcnt lgkmcnt(5)
	v_fmac_f32_e32 v12, v11, v4
	s_waitcnt lgkmcnt(4)
	v_fmac_f32_e32 v13, v12, v5
	s_waitcnt lgkmcnt(3)
	v_fmac_f32_e32 v14, v13, v6
	s_waitcnt lgkmcnt(2)
	v_fmac_f32_e32 v15, v14, v7
	s_waitcnt lgkmcnt(1)
	v_fmac_f32_e32 v16, v15, v8
	v_mul_f32_e32 v2, v2, v3
	s_waitcnt lgkmcnt(0)
	v_fmac_f32_e32 v18, v16, v9
	ds_read2st64_b32 v[10:11], v133 offset0:144 offset1:145
	ds_read2st64_b32 v[12:13], v133 offset0:146 offset1:147
	ds_read2st64_b32 v[14:15], v133 offset0:148 offset1:149
	ds_read2st64_b32 v[16:17], v133 offset0:150 offset1:151
	ds_read_b32 v3, v174
	ds_read_b32 v19, v175
	ds_read_b32 v21, v176
	ds_read_b32 v23, v177
	ds_read_b32 v25, v178
	ds_read_b32 v27, v179
	ds_read_b32 v29, v186
	ds_read_b32 v31, v187
	s_waitcnt lgkmcnt(7)
	v_fmac_f32_e32 v3, v18, v10
	v_mov_b32_e32 v32, v4
	v_mov_b32_e32 v33, v11
	v_mov_b32_e32 v18, v5
	v_mul_f32_e32 v4, v2, v4
	s_waitcnt lgkmcnt(6)
	v_pk_fma_f32 v[2:3], v[2:3], v[32:33], v[18:19]
	v_mul_f32_e32 v4, v4, v5
	v_mov_b32_e32 v5, v3
	v_mov_b32_e32 v2, v6
	v_mov_b32_e32 v3, v12
	v_pk_mul_f32 v[18:19], v[4:5], v[2:3]
	v_mov_b32_e32 v6, v7
	v_mov_b32_e32 v20, v7
	v_pk_mul_f32 v[6:7], v[18:19], v[6:7]
	s_waitcnt lgkmcnt(5)
	v_pk_fma_f32 v[2:3], v[4:5], v[2:3], v[20:21]
	v_mov_b32_e32 v4, v8
	v_mov_b32_e32 v2, v6
	v_mov_b32_e32 v5, v13
	v_pk_mul_f32 v[6:7], v[6:7], v[8:9]
	v_mov_b32_e32 v8, v9
	v_mov_b32_e32 v22, v9
	v_pk_mul_f32 v[6:7], v[6:7], v[8:9]
	s_waitcnt lgkmcnt(4)
	v_pk_fma_f32 v[2:3], v[2:3], v[4:5], v[22:23]
	v_mov_b32_e32 v8, v11
	v_mov_b32_e32 v7, v3
	v_mov_b32_e32 v2, v10
	v_mov_b32_e32 v3, v14
	v_pk_mul_f32 v[4:5], v[6:7], v[2:3]
	v_mov_b32_e32 v24, v11
	v_pk_mul_f32 v[4:5], v[4:5], v[8:9]
	s_waitcnt lgkmcnt(3)
	v_pk_fma_f32 v[2:3], v[6:7], v[2:3], v[24:25]
	v_mov_b32_e32 v6, v12
	v_mov_b32_e32 v2, v4
	v_mov_b32_e32 v7, v15
	v_pk_mul_f32 v[4:5], v[4:5], v[12:13]
	v_mov_b32_e32 v8, v13
	v_mov_b32_e32 v26, v13
	v_pk_mul_f32 v[4:5], v[4:5], v[8:9]
	s_waitcnt lgkmcnt(2)
	v_pk_fma_f32 v[2:3], v[2:3], v[6:7], v[26:27]
	v_mov_b32_e32 v8, v15
	v_mov_b32_e32 v5, v3
	v_mov_b32_e32 v2, v14
	v_mov_b32_e32 v3, v16
	v_pk_mul_f32 v[6:7], v[4:5], v[2:3]
	v_mov_b32_e32 v28, v15
	v_pk_mul_f32 v[6:7], v[6:7], v[8:9]
	s_waitcnt lgkmcnt(1)
	v_pk_fma_f32 v[2:3], v[4:5], v[2:3], v[28:29]
	v_pk_mul_f32 v[4:5], v[6:7], v[16:17]
	v_mov_b32_e32 v2, v6
	v_mov_b32_e32 v6, v17
	v_mov_b32_e32 v30, v17
	v_pk_mul_f32 v[4:5], v[4:5], v[6:7]
	s_waitcnt lgkmcnt(0)
	v_pk_fma_f32 v[2:3], v[2:3], v[16:17], v[30:31]
	s_nop 0
	v_mov_b32_e32 v5, v3
	ds_write_b64 v131, v[4:5]
	s_waitcnt lgkmcnt(0)
	s_barrier
; __device__ __forceinline__ unsigned f2bf(float f) { unsigned u = __builtin_bit_cast(unsigned, f); return (u + 0x7fffu + ((u >> 16) & 1u)) >> 16; }
; __device__ __forceinline__ void rglru_unit(const Params& P, int l, int unit, LAS unsigned char* lds, bool dry = false) {
;     ...
;           float hin = carry, hn = carry;
; #pragma unroll
;           for (int s2 = 0; s2 < 8; ++s2) { if (s2 == s) hin = hn; const f32x2 sg = seg[s2 * 64 + c]; hn = sg.x * hn + sg.y; }
;           carry = hn;
;           float h = hin;
; #pragma unroll
;           for (int k = 0; k < 16; ++k) { const float a = Ab[(16 * s + k) * 64 + c], u = Ub[(16 * s + k) * 64 + c]; h = a * h + u;
;               const float gg = bf2f(gq[k]); gp[(size_t)k * XP] = (bf16_t)f2bf(dry ? gg : gg * h); }
	ds_read2st64_b64 v[2:5], v132 offset1:1
	ds_read2st64_b64 v[6:9], v132 offset0:2 offset1:3
	s_waitcnt lgkmcnt(1)
	v_fma_f32 v2, v89, v2, v3
	v_cndmask_b32_e64 v3, v89, v2, s[6:7]
	v_fmac_f32_e32 v5, v4, v2
	v_cndmask_b32_e64 v10, v3, v5, s[8:9]
	s_waitcnt lgkmcnt(0)
	v_fma_f32 v6, v6, v5, v7
	ds_read2st64_b64 v[2:5], v132 offset0:4 offset1:5
	ds_read2st64_b64 v[86:89], v132 offset0:6 offset1:7
	v_cndmask_b32_e64 v7, v10, v6, s[10:11]
	v_fmac_f32_e32 v9, v8, v6
	v_cndmask_b32_e64 v6, v7, v9, s[12:13]
	s_waitcnt lgkmcnt(1)
	v_fma_f32 v2, v2, v9, v3
	v_cndmask_b32_e64 v3, v6, v2, s[14:15]
	v_fmac_f32_e32 v5, v4, v2
	v_cndmask_b32_e64 v2, v3, v5, s[16:17]
	s_waitcnt lgkmcnt(0)
	v_fma_f32 v10, v86, v5, v87
	v_cndmask_b32_e64 v11, v2, v10, s[18:19]
	ds_read2st64_b32 v[2:3], v133 offset0:136 offset1:137
	ds_read2st64_b32 v[4:5], v133 offset0:138 offset1:139
	ds_read2st64_b32 v[6:7], v133 offset0:140 offset1:141
	ds_read2st64_b32 v[8:9], v133 offset0:142 offset1:143
	ds_read_b32 v12, v166
	ds_read_b32 v13, v167
	ds_read_b32 v14, v168
	ds_read_b32 v15, v169
	ds_read_b32 v16, v170
	ds_read_b32 v17, v171
	ds_read_b32 v18, v172
	ds_read_b32 v19, v173
	s_waitcnt lgkmcnt(7)
	v_fmac_f32_e32 v12, v2, v11
	v_lshlrev_b32_e32 v2, 16, v207
	v_mul_f32_e32 v2, v12, v2
	v_bfe_u32 v11, v2, 16, 1
	v_add3_u32 v2, v2, v11, s60
	global_store_short_d16_hi v[126:127], v2, off
	s_waitcnt lgkmcnt(0)
	v_fmac_f32_e32 v13, v3, v12
	v_lshlrev_b32_e32 v2, 16, v206
	v_mul_f32_e32 v2, v13, v2
	v_bfe_u32 v3, v2, 16, 1
	v_add3_u32 v2, v2, v3, s60
	global_store_short_d16_hi v[126:127], v2, off offset:2048
	v_fmac_f32_e32 v14, v4, v13
	v_lshlrev_b32_e32 v2, 16, v205
	v_mul_f32_e32 v2, v14, v2
	v_bfe_u32 v3, v2, 16, 1
	v_add3_u32 v2, v2, v3, s60
	global_store_short_d16_hi v[124:125], v2, off
	v_fmac_f32_e32 v15, v5, v14
	v_lshlrev_b32_e32 v2, 16, v204
	v_mul_f32_e32 v2, v15, v2
	v_bfe_u32 v3, v2, 16, 1
	v_add3_u32 v2, v2, v3, s60
	global_store_short_d16_hi v[124:125], v2, off offset:2048
	v_fmac_f32_e32 v16, v6, v15
	v_lshlrev_b32_e32 v2, 16, v203
	v_mul_f32_e32 v2, v16, v2
	v_bfe_u32 v3, v2, 16, 1
	v_add3_u32 v2, v2, v3, s60
	global_store_short_d16_hi v[122:123], v2, off
	v_fmac_f32_e32 v17, v7, v16
	v_lshlrev_b32_e32 v2, 16, v202
	v_mul_f32_e32 v2, v17, v2
	v_bfe_u32 v3, v2, 16, 1
	v_add3_u32 v2, v2, v3, s60
	global_store_short_d16_hi v[122:123], v2, off offset:2048
	v_fmac_f32_e32 v18, v8, v17
	v_lshlrev_b32_e32 v2, 16, v201
	v_mul_f32_e32 v2, v18, v2
	v_bfe_u32 v3, v2, 16, 1
	v_add3_u32 v2, v2, v3, s60
	global_store_short_d16_hi v[120:121], v2, off
	v_fmac_f32_e32 v19, v9, v18
	v_lshlrev_b32_e32 v2, 16, v200
	v_mul_f32_e32 v2, v19, v2
	v_bfe_u32 v3, v2, 16, 1
	v_add3_u32 v2, v2, v3, s60
	global_store_short_d16_hi v[120:121], v2, off offset:2048
	ds_read2st64_b32 v[2:3], v133 offset0:144 offset1:145
	ds_read2st64_b32 v[4:5], v133 offset0:146 offset1:147
	ds_read2st64_b32 v[6:7], v133 offset0:148 offset1:149
	ds_read2st64_b32 v[8:9], v133 offset0:150 offset1:151
	ds_read_b32 v11, v174
	ds_read_b32 v12, v175
	ds_read_b32 v13, v176
	ds_read_b32 v14, v177
	ds_read_b32 v15, v178
	ds_read_b32 v16, v179
	ds_read_b32 v17, v186
	ds_read_b32 v18, v187
	s_waitcnt lgkmcnt(0)
	v_fmac_f32_e32 v11, v19, v2
	v_lshlrev_b32_e32 v2, 16, v199
	v_mul_f32_e32 v2, v11, v2
	v_bfe_u32 v19, v2, 16, 1
	v_add3_u32 v2, v2, v19, s60
	global_store_short_d16_hi v[118:119], v2, off
	v_fmac_f32_e32 v12, v11, v3
	v_lshlrev_b32_e32 v2, 16, v198
	v_mul_f32_e32 v2, v12, v2
	v_bfe_u32 v3, v2, 16, 1
	v_add3_u32 v2, v2, v3, s60
	global_store_short_d16_hi v[118:119], v2, off offset:2048
	v_fmac_f32_e32 v13, v12, v4
	v_lshlrev_b32_e32 v2, 16, v197
	v_mul_f32_e32 v2, v13, v2
	v_bfe_u32 v3, v2, 16, 1
	v_add3_u32 v2, v2, v3, s60
	global_store_short_d16_hi v[116:117], v2, off
	v_fmac_f32_e32 v14, v13, v5
	v_lshlrev_b32_e32 v2, 16, v196
	v_mul_f32_e32 v2, v14, v2
	v_bfe_u32 v3, v2, 16, 1
	v_add3_u32 v2, v2, v3, s60
	global_store_short_d16_hi v[116:117], v2, off offset:2048
	v_fmac_f32_e32 v15, v14, v6
	v_lshlrev_b32_e32 v2, 16, v195
	v_mul_f32_e32 v2, v15, v2
	v_bfe_u32 v3, v2, 16, 1
	v_add3_u32 v2, v2, v3, s60
	global_store_short_d16_hi v[114:115], v2, off
	v_fmac_f32_e32 v16, v15, v7
	v_lshlrev_b32_e32 v2, 16, v194
	v_mul_f32_e32 v2, v16, v2
	v_bfe_u32 v3, v2, 16, 1
	v_add3_u32 v2, v2, v3, s60
	global_store_short_d16_hi v[114:115], v2, off offset:2048
	v_fmac_f32_e32 v17, v16, v8
	v_lshlrev_b32_e32 v2, 16, v111
	v_mul_f32_e32 v2, v17, v2
	v_bfe_u32 v3, v2, 16, 1
	v_fmac_f32_e32 v18, v17, v9
	v_add3_u32 v2, v2, v3, s60
	v_mul_f32_e32 v1, v18, v1
	global_store_short_d16_hi v[112:113], v2, off
	v_bfe_u32 v2, v1, 16, 1
	v_add3_u32 v1, v1, v2, s60
	v_fmac_f32_e32 v89, v88, v10
	global_store_short_d16_hi v[112:113], v1, off offset:2048
	s_cbranch_scc0 .LBB0_346
